# Q GEMM -> attention fused per workgroup (own Q tile, WG-local sync, no grid barrier)
# speedup vs baseline: 1.0126x; 1.0046x over previous
.LBB0_1788:
	s_cmp_lt_i32 s78, 15
	s_cselect_b64 s[0:1], -1, 0
	s_and_b64 s[4:5], s[0:1], s[4:5]
	s_andn2_b64 vcc, exec, s[4:5]
	s_cbranch_vccnz .LBB0_1812
	s_and_b32 s12, s2, 7
	s_lshl_b32 s12, s12, 5
	s_lshr_b32 s13, s2, 3
	s_add_u32 s12, s12, s13
	s_lshr_b32 s13, s12, 4
	s_lshl_b32 s13, s13, 2
	s_and_b32 s14, s12, 3
	s_add_u32 s13, s13, s14
	s_lshr_b32 s14, s12, 2
	s_and_b32 s14, s14, 3
	s_lshr_b32 s15, s13, 4
	s_lshl_b32 s15, s15, 11
	s_lshl_b32 s14, s14, 9
	s_add_u32 s15, s15, s14
	s_and_b32 s13, s13, 15
	s_lshl_b32 s13, s13, 3
	s_add_u32 s15, s15, s13
	v_readlane_b32 s13, v242, 37
	s_add_u32 s33, s15, s13
	s_add_u32 s100, s33, 0x200
	s_cmpk_gt_i32 s33, 0x1fff
	s_cbranch_scc1 .LBB0_1812
	v_lshrrev_b32_e32 v6, 5, v184
	s_waitcnt lgkmcnt(0)
	v_and_b32_e32 v1, 3, v185
	v_and_b32_e32 v2, 12, v185
	v_lshlrev_b32_e32 v4, 1, v6
	v_writelane_b32 v242, s84, 3
	v_lshl_or_b32 v3, v1, 4, v2
	v_bitop3_b32 v5, v4, v1, 1 bitop3:0x36
	v_bitop3_b32 v4, v4, v185, 3 bitop3:0x78
	v_readlane_b32 s3, v242, 37
	v_or_b32_e32 v5, v5, v3
	v_or_b32_e32 v3, v4, v3
	v_lshlrev_b32_e32 v4, 2, v185
	s_mul_i32 s4, s3, 0x4200
	s_add_u32 s3, s76, 0x8500000
	v_and_b32_e32 v4, 16, v4
	v_lshrrev_b32_e32 v7, 1, v184
	s_addc_u32 s66, s77, 0
	v_and_or_b32 v4, v7, 8, v4
	v_and_b32_e32 v7, 4, v7
	s_add_u32 s40, s76, 0xbd00000
	v_or_b32_e32 v8, v7, v1
	s_addc_u32 s41, s77, 0
	s_add_i32 s67, s4, 0
	v_lshlrev_b32_e32 v0, 6, v185
	v_lshrrev_b32_e32 v4, 3, v4
	v_lshlrev_b32_e32 v8, 7, v8
	s_movk_i32 s4, 0x440
	v_and_b32_e32 v0, 0x400, v0
	v_mad_u32_u24 v4, v4, s4, v8
	v_or_b32_e32 v8, 6, v6
	v_or_b32_e32 v9, 4, v6
	v_or_b32_e32 v10, 2, v6
	v_bitop3_b32 v8, v7, v8, v1 bitop3:0x36
	v_bitop3_b32 v9, v7, v9, v1 bitop3:0x36
	v_bitop3_b32 v10, v7, v10, v1 bitop3:0x36
	v_bitop3_b32 v1, v7, v6, v1 bitop3:0x36
	v_lshl_add_u32 v7, v5, 4, v0
	v_lshrrev_b32_e32 v5, 4, v184
	v_lshrrev_b32_e32 v84, 3, v184
	v_or_b32_e32 v11, v5, v2
	v_lshl_add_u32 v8, v8, 4, v4
	v_lshl_add_u32 v9, v9, 4, v4
	v_lshl_add_u32 v10, v10, 4, v4
	v_lshl_add_u32 v1, v1, 4, v4
	v_mov_b32_e32 v83, 0
	v_bitop3_b32 v4, v84, v185, 7 bitop3:0x78
	v_bitop3_b32 v12, v5, v185, 3 bitop3:0x78
	v_lshlrev_b32_e32 v82, 13, v11
	v_lshlrev_b32_e32 v2, 3, v4
	v_lshl_add_u64 v[4:5], s[76:77], 0, v[82:83]
	v_lshlrev_b32_e32 v82, 4, v12
	v_lshl_add_u64 v[4:5], v[4:5], 0, v[82:83]
	s_mov_b64 s[4:5], 0xdd00000
	v_lshl_or_b32 v3, v3, 4, v0
	v_and_b32_e32 v80, 31, v185
	v_lshlrev_b32_e32 v0, 3, v6
	v_lshl_add_u64 v[86:87], v[4:5], 0, s[4:5]
	v_lshlrev_b32_e32 v4, 4, v6
	v_sub_u32_e32 v4, v80, v4
	v_lshlrev_b32_e32 v90, 1, v0
	v_mbcnt_lo_u32_b32 v0, -1, 0
	s_mov_b32 s45, 0
	v_cmp_lt_i32_e64 s[4:5], 0, v4
	v_cmp_lt_i32_e64 s[6:7], 1, v4
	v_cmp_lt_i32_e64 s[8:9], 2, v4
	v_cmp_lt_i32_e64 s[10:11], 3, v4
	v_cmp_lt_i32_e64 s[12:13], 4, v4
	v_cmp_lt_i32_e64 s[14:15], 5, v4
	v_cmp_lt_i32_e64 s[16:17], 6, v4
	v_cmp_lt_i32_e64 s[18:19], 7, v4
	v_cmp_lt_i32_e64 s[20:21], 8, v4
	v_cmp_lt_i32_e64 s[22:23], 9, v4
	v_cmp_lt_i32_e64 s[24:25], 10, v4
	v_cmp_lt_i32_e64 s[26:27], 11, v4
	v_cmp_lt_i32_e64 s[28:29], 12, v4
	v_cmp_lt_i32_e64 s[30:31], 13, v4
	v_cmp_lt_i32_e64 s[34:35], 14, v4
	v_cmp_lt_i32_e64 s[36:37], 15, v4
	v_cmp_gt_u32_e64 s[38:39], 32, v184
	v_lshlrev_b32_e32 v88, 13, v6
	v_mov_b32_e32 v89, v83
	v_mov_b32_e32 v91, v83
	v_lshlrev_b32_e32 v92, 1, v2
	v_mov_b32_e32 v93, v83
	s_mov_b64 s[46:47], 0x4000
	s_add_i32 s70, s67, 0x440
	s_mov_b64 s[48:49], 0x8000
	s_add_i32 s71, s67, 0x880
	s_mov_b64 s[50:51], 0xc000
	s_add_i32 s72, s67, 0xcc0
	s_add_i32 s73, s67, 0x1100
	s_mov_b64 s[52:53], 0x20000
	s_add_i32 s74, s67, 0x1500
	s_mov_b64 s[54:55], 0x40000
	s_add_i32 s75, s67, 0x1900
	s_mov_b64 s[56:57], 0x60000
	s_add_i32 s80, s67, 0x1d00
	s_add_i32 s81, s67, 0x2100
	s_add_i32 s84, s67, 0x2540
	s_add_i32 s85, s67, 0x2980
	s_add_i32 s86, s67, 0x2dc0
	s_add_i32 s87, s67, 0x3200
	s_add_i32 s88, s67, 0x3600
	s_add_i32 s89, s67, 0x3a00
	s_add_i32 s90, s67, 0x3e00
	v_add_u32_e32 v81, s67, v1
	v_add_u32_e32 v85, s67, v10
	v_add_u32_e32 v116, s67, v9
	v_add_u32_e32 v117, s67, v8
	v_add_u32_e32 v118, s67, v3
	v_add_u32_e32 v119, s67, v7
	s_mov_b32 s91, 0xff61b1e6
	s_mov_b32 s92, 0x40e66666
	s_mov_b32 s93, 0x1f7ff3c8
	v_mbcnt_hi_u32_b32 v120, -1, v0
	s_branch .LBB0_1792
.LBB0_1791:
	s_lshl_b64 s[42:43], s[60:61], 11
	s_add_u32 s42, s3, s42
	s_addc_u32 s43, s66, s43
	s_add_u32 s42, s42, s62
	s_addc_u32 s43, s43, s63
	v_lshlrev_b32_e32 v82, 1, v80
	v_lshl_add_u64 v[32:33], s[42:43], 0, v[82:83]
	s_nop 0
	v_cvt_pk_bf16_f32 v0, v0, s0
	v_lshl_add_u64 v[32:33], v[32:33], 0, v[88:89]
	s_waitcnt vmcnt(0)
	global_store_short v[32:33], v0, off
	v_cvt_pk_bf16_f32 v0, v16, s0
	global_store_short v[32:33], v0, off offset:64
	v_cvt_pk_bf16_f32 v0, v1, s0
	global_store_short v[32:33], v0, off offset:2048
	v_cvt_pk_bf16_f32 v0, v17, s0
	s_movk_i32 s42, 0x1000
	global_store_short v[32:33], v0, off offset:2112
	v_add_co_u32_e32 v0, vcc, s42, v32
	v_cvt_pk_bf16_f32 v2, v2, s0
	s_nop 0
	v_addc_co_u32_e32 v1, vcc, 0, v33, vcc
	global_store_short v[0:1], v2, off
	v_cvt_pk_bf16_f32 v2, v18, s0
	global_store_short v[0:1], v2, off offset:64
	v_cvt_pk_bf16_f32 v2, v3, s0
	global_store_short v[0:1], v2, off offset:2048
	v_cvt_pk_bf16_f32 v2, v19, s0
	s_movk_i32 s42, 0x4000
	global_store_short v[0:1], v2, off offset:2112
	v_add_co_u32_e32 v0, vcc, s42, v32
	s_movk_i32 s42, 0x5000
	s_nop 0
	v_addc_co_u32_e32 v1, vcc, 0, v33, vcc
	v_add_co_u32_e32 v2, vcc, s42, v32
	v_cvt_pk_bf16_f32 v4, v4, s0
	s_nop 0
	v_addc_co_u32_e32 v3, vcc, 0, v33, vcc
	global_store_short v[2:3], v4, off offset:-4096
	v_cvt_pk_bf16_f32 v4, v20, s0
	global_store_short v[0:1], v4, off offset:64
	v_cvt_pk_bf16_f32 v4, v5, s0
	global_store_short v[0:1], v4, off offset:2048
	v_cvt_pk_bf16_f32 v4, v21, s0
	global_store_short v[0:1], v4, off offset:2112
	v_cvt_pk_bf16_f32 v0, v6, s0
	global_store_short v[2:3], v0, off
	v_cvt_pk_bf16_f32 v0, v22, s0
	global_store_short v[2:3], v0, off offset:64
	v_cvt_pk_bf16_f32 v0, v7, s0
	global_store_short v[2:3], v0, off offset:2048
	v_cvt_pk_bf16_f32 v0, v23, s0
	s_mov_b32 s42, 0x8000
	global_store_short v[2:3], v0, off offset:2112
	v_add_co_u32_e32 v0, vcc, s42, v32
	s_mov_b32 s42, 0x9000
	s_nop 0
	v_addc_co_u32_e32 v1, vcc, 0, v33, vcc
	v_add_co_u32_e32 v2, vcc, s42, v32
	v_cvt_pk_bf16_f32 v4, v8, s0
	s_nop 0
	v_addc_co_u32_e32 v3, vcc, 0, v33, vcc
	global_store_short v[2:3], v4, off offset:-4096
	v_cvt_pk_bf16_f32 v4, v24, s0
	global_store_short v[0:1], v4, off offset:64
	v_cvt_pk_bf16_f32 v4, v9, s0
	global_store_short v[0:1], v4, off offset:2048
	v_cvt_pk_bf16_f32 v4, v25, s0
	global_store_short v[0:1], v4, off offset:2112
	v_cvt_pk_bf16_f32 v0, v10, s0
	global_store_short v[2:3], v0, off
	v_cvt_pk_bf16_f32 v0, v26, s0
	global_store_short v[2:3], v0, off offset:64
	v_cvt_pk_bf16_f32 v0, v11, s0
	global_store_short v[2:3], v0, off offset:2048
	v_cvt_pk_bf16_f32 v0, v27, s0
	s_mov_b32 s42, 0xc000
	global_store_short v[2:3], v0, off offset:2112
	v_add_co_u32_e32 v0, vcc, s42, v32
	s_mov_b32 s42, 0xd000
	s_nop 0
	v_addc_co_u32_e32 v1, vcc, 0, v33, vcc
	v_add_co_u32_e32 v2, vcc, s42, v32
	v_cvt_pk_bf16_f32 v4, v12, s0
	s_nop 0
	v_addc_co_u32_e32 v3, vcc, 0, v33, vcc
	global_store_short v[2:3], v4, off offset:-4096
	v_cvt_pk_bf16_f32 v4, v28, s0
	global_store_short v[0:1], v4, off offset:64
	v_cvt_pk_bf16_f32 v4, v13, s0
	global_store_short v[0:1], v4, off offset:2048
	v_cvt_pk_bf16_f32 v4, v29, s0
	global_store_short v[0:1], v4, off offset:2112
	v_cvt_pk_bf16_f32 v0, v14, s0
	global_store_short v[2:3], v0, off
	v_cvt_pk_bf16_f32 v0, v30, s0
	v_readlane_b32 s42, v242, 38
	global_store_short v[2:3], v0, off offset:64
	v_cvt_pk_bf16_f32 v0, v15, s0
	s_add_i32 s33, s33, 0x80
	global_store_short v[2:3], v0, off offset:2048
	v_cvt_pk_bf16_f32 v0, v31, s0
	s_cmp_lt_i32 s33, s100
	v_readlane_b32 s43, v242, 39
	global_store_short v[2:3], v0, off offset:2112
	s_cbranch_scc0 .LBB0_1811
